# v28 + grid barrier: XCD-last blocks issue their L1 invalidate right after the top-level arrival atomic (overlapping that round trip) instead of ahead of the L2 write-back; other blocks invalidate befo
# speedup vs baseline: 1.0073x; 1.0073x over previous
.LBB0_1900:
	s_or_b64 exec, exec, s[20:21]
	v_cvt_f32_u32_e32 v4, v2
	s_waitcnt vmcnt(0)
	v_readfirstlane_b32 s20, v3
	v_sub_u32_e32 v3, 0, v2
	v_rcp_iflag_f32_e32 v4, v4
	v_add_u32_e32 v5, s20, v1
	v_mul_f32_e32 v4, 0x4f7ffffe, v4
	v_cvt_u32_f32_e32 v4, v4
	v_mul_lo_u32 v1, v3, v4
	v_mul_hi_u32 v1, v4, v1
	v_add_u32_e32 v1, v4, v1
	v_mul_hi_u32 v1, v5, v1
	v_mul_lo_u32 v3, v1, v2
	v_sub_u32_e32 v3, v5, v3
	v_add_u32_e32 v4, 1, v1
	v_cmp_ge_u32_e32 vcc, v3, v2
	s_nop 1
	v_cndmask_b32_e32 v1, v1, v4, vcc
	v_sub_u32_e32 v4, v3, v2
	v_cndmask_b32_e32 v3, v3, v4, vcc
	v_add_u32_e32 v4, 1, v1
	v_cmp_ge_u32_e32 vcc, v3, v2
	v_add_u32_e32 v3, 1, v5
	s_nop 0
	v_cndmask_b32_e32 v1, v1, v4, vcc
	v_mul_lo_u32 v4, v2, v1
	v_add_u32_e32 v2, v4, v2
	v_cmp_ne_u32_e32 vcc, v3, v2
	s_and_saveexec_b64 s[20:21], vcc
	s_xor_b64 s[20:21], exec, s[20:21]
	s_cbranch_execz .LBB0_1914
	buffer_inv sc1
	v_readlane_b32 s24, v233, 40
	v_readlane_b32 s25, v233, 41
	s_waitcnt lgkmcnt(0)
	s_nop 3
	global_load_dword v0, v33, s[24:25] sc1
	s_waitcnt vmcnt(0)
	v_cmp_eq_u32_e32 vcc, v0, v1
	s_and_saveexec_b64 s[28:29], vcc
	s_cbranch_execz .LBB0_1913
	s_mov_b32 s24, 1
	s_mov_b64 s[36:37], 0
	s_branch .LBB0_1904

.LBB0_1914:
	s_andn2_saveexec_b64 s[20:21], s[20:21]
	s_cbranch_execz .LBB0_1934
	s_mov_b64 s[20:21], exec
	buffer_wbl2 sc1
	s_waitcnt lgkmcnt(0)
	s_waitcnt vmcnt(0)
	v_mbcnt_lo_u32_b32 v1, s20, 0
	v_mbcnt_hi_u32_b32 v1, s21, v1
	v_cmp_eq_u32_e32 vcc, 0, v1
	s_and_saveexec_b64 s[28:29], vcc
	s_cbranch_execz .LBB0_1917
	s_bcnt1_i32_b64 s20, s[20:21]
	v_mov_b32_e32 v2, s20
	v_readlane_b32 s20, v233, 38
	v_readlane_b32 s21, v233, 39
	s_nop 4
	global_atomic_add v2, v33, v2, s[20:21] sc0
	buffer_inv sc1
.LBB0_1917:
	s_or_b64 exec, exec, s[28:29]
	s_waitcnt vmcnt(1)
	v_readfirstlane_b32 s20, v2
	v_cvt_f32_u32_e32 v2, v0
	v_sub_u32_e32 v3, 0, v0
	v_add_u32_e32 v1, s20, v1
	v_readlane_b32 s20, v233, 40
	v_rcp_iflag_f32_e32 v2, v2
	v_readlane_b32 s21, v233, 41
	s_mov_b64 s[28:29], -1
	v_mul_f32_e32 v2, 0x4f7ffffe, v2
	v_cvt_u32_f32_e32 v2, v2
	v_mul_lo_u32 v3, v3, v2
	v_mul_hi_u32 v3, v2, v3
	v_add_u32_e32 v2, v2, v3
	v_mul_hi_u32 v2, v1, v2
	v_mul_lo_u32 v3, v2, v0
	v_sub_u32_e32 v3, v1, v3
	v_cmp_ge_u32_e32 vcc, v3, v0
	v_add_u32_e32 v4, 1, v2
	v_add_u32_e32 v1, 1, v1
	v_cndmask_b32_e32 v2, v2, v4, vcc
	v_sub_u32_e32 v4, v3, v0
	v_cndmask_b32_e32 v3, v3, v4, vcc
	v_cmp_ge_u32_e32 vcc, v3, v0
	v_add_u32_e32 v3, 1, v2
	s_nop 0
	v_cndmask_b32_e32 v2, v2, v3, vcc
	v_mul_lo_u32 v3, v0, v2
	v_add_u32_e32 v0, v3, v0
	v_cmp_ne_u32_e32 vcc, v1, v0
	v_mov_b64_e32 v[0:1], s[20:21]
	s_and_saveexec_b64 s[20:21], vcc
	s_cbranch_execz .LBB0_1929
	v_readlane_b32 s24, v233, 40
	v_readlane_b32 s25, v233, 41
	s_mov_b64 s[36:37], 0
	s_nop 3
	global_load_dword v0, v33, s[24:25] sc1
	s_waitcnt vmcnt(0)
	v_cmp_eq_u32_e32 vcc, v0, v2
	s_and_saveexec_b64 s[28:29], vcc
	s_cbranch_execz .LBB0_1928
	s_mov_b32 s24, 1
	s_branch .LBB0_1921
